# GEMM K-loop heads aligned to 64 bytes (on top of the previous version)
# baseline (speedup 1.0000x reference)
.LBB0_97:
	s_ashr_i32 s7, s6, 31
	s_lshl_b64 s[10:11], s[6:7], 19
	v_readlane_b32 s14, v255, 9
	v_readlane_b32 s15, v255, 10
	s_add_u32 s16, s14, s10
	s_addc_u32 s17, s15, s11
	s_and_b64 s[10:11], s[38:39], exec
	s_cselect_b32 s7, s17, s45
	s_cselect_b32 s10, s16, s44
	s_ashr_i32 s5, s4, 31
	s_lshl_b64 s[14:15], s[4:5], 19
	s_add_u32 s40, s26, s14
	s_addc_u32 s41, s27, s15
	s_and_b64 s[14:15], s[38:39], exec
	s_cselect_b32 s5, s41, s47
	s_cselect_b32 s11, s40, s46
	s_add_u32 s44, s44, 0x40080
	s_addc_u32 s45, s45, 0
	s_add_u32 s13, s46, 0x100
	v_mov_b32_e32 v4, 0
	s_addc_u32 s14, s47, 0
	s_mov_b32 s15, -2
	v_mov_b32_e32 v5, v4
	v_mov_b32_e32 v6, v4
	v_mov_b32_e32 v7, v4
	v_mov_b32_e32 v12, v4
	v_mov_b32_e32 v13, v4
	v_mov_b32_e32 v14, v4
	v_mov_b32_e32 v15, v4
	v_mov_b32_e32 v20, v4
	v_mov_b32_e32 v21, v4
	v_mov_b32_e32 v22, v4
	v_mov_b32_e32 v23, v4
	v_mov_b32_e32 v28, v4
	v_mov_b32_e32 v29, v4
	v_mov_b32_e32 v30, v4
	v_mov_b32_e32 v31, v4
	v_mov_b32_e32 v36, v4
	v_mov_b32_e32 v37, v4
	v_mov_b32_e32 v38, v4
	v_mov_b32_e32 v39, v4
	v_mov_b32_e32 v44, v4
	v_mov_b32_e32 v45, v4
	v_mov_b32_e32 v46, v4
	v_mov_b32_e32 v47, v4
	v_mov_b32_e32 v52, v4
	v_mov_b32_e32 v53, v4
	v_mov_b32_e32 v54, v4
	v_mov_b32_e32 v55, v4
	v_mov_b32_e32 v60, v4
	v_mov_b32_e32 v61, v4
	v_mov_b32_e32 v62, v4
	v_mov_b32_e32 v63, v4
	v_mov_b32_e32 v8, v4
	v_mov_b32_e32 v9, v4
	v_mov_b32_e32 v10, v4
	v_mov_b32_e32 v11, v4
	v_mov_b32_e32 v16, v4
	v_mov_b32_e32 v17, v4
	v_mov_b32_e32 v18, v4
	v_mov_b32_e32 v19, v4
	v_mov_b32_e32 v24, v4
	v_mov_b32_e32 v25, v4
	v_mov_b32_e32 v26, v4
	v_mov_b32_e32 v27, v4
	v_mov_b32_e32 v32, v4
	v_mov_b32_e32 v33, v4
	v_mov_b32_e32 v34, v4
	v_mov_b32_e32 v35, v4
	v_mov_b32_e32 v40, v4
	v_mov_b32_e32 v41, v4
	v_mov_b32_e32 v42, v4
	v_mov_b32_e32 v43, v4
	v_mov_b32_e32 v48, v4
	v_mov_b32_e32 v49, v4
	v_mov_b32_e32 v50, v4
	v_mov_b32_e32 v51, v4
	v_mov_b32_e32 v56, v4
	v_mov_b32_e32 v57, v4
	v_mov_b32_e32 v58, v4
	v_mov_b32_e32 v59, v4
	v_mov_b32_e32 v64, v4
	v_mov_b32_e32 v65, v4
	v_mov_b32_e32 v66, v4
	v_mov_b32_e32 v67, v4
	v_mov_b32_e32 v68, v4
	v_mov_b32_e32 v69, v4
	v_mov_b32_e32 v70, v4
	v_mov_b32_e32 v71, v4
	v_mov_b32_e32 v76, v4
	v_mov_b32_e32 v77, v4
	v_mov_b32_e32 v78, v4
	v_mov_b32_e32 v79, v4
	v_mov_b32_e32 v84, v4
	v_mov_b32_e32 v85, v4
	v_mov_b32_e32 v86, v4
	v_mov_b32_e32 v87, v4
	v_mov_b32_e32 v92, v4
	v_mov_b32_e32 v93, v4
	v_mov_b32_e32 v94, v4
	v_mov_b32_e32 v95, v4
	v_mov_b32_e32 v100, v4
	v_mov_b32_e32 v101, v4
	v_mov_b32_e32 v102, v4
	v_mov_b32_e32 v103, v4
	v_mov_b32_e32 v108, v4
	v_mov_b32_e32 v109, v4
	v_mov_b32_e32 v110, v4
	v_mov_b32_e32 v111, v4
	v_mov_b32_e32 v116, v4
	v_mov_b32_e32 v117, v4
	v_mov_b32_e32 v118, v4
	v_mov_b32_e32 v119, v4
	v_mov_b32_e32 v124, v4
	v_mov_b32_e32 v125, v4
	v_mov_b32_e32 v126, v4
	v_mov_b32_e32 v127, v4
	v_mov_b32_e32 v72, v4
	v_mov_b32_e32 v73, v4
	v_mov_b32_e32 v74, v4
	v_mov_b32_e32 v75, v4
	v_mov_b32_e32 v80, v4
	v_mov_b32_e32 v81, v4
	v_mov_b32_e32 v82, v4
	v_mov_b32_e32 v83, v4
	v_mov_b32_e32 v88, v4
	v_mov_b32_e32 v89, v4
	v_mov_b32_e32 v90, v4
	v_mov_b32_e32 v91, v4
	v_mov_b32_e32 v96, v4
	v_mov_b32_e32 v97, v4
	v_mov_b32_e32 v98, v4
	v_mov_b32_e32 v99, v4
	v_mov_b32_e32 v104, v4
	v_mov_b32_e32 v105, v4
	v_mov_b32_e32 v106, v4
	v_mov_b32_e32 v107, v4
	v_mov_b32_e32 v112, v4
	v_mov_b32_e32 v113, v4
	v_mov_b32_e32 v114, v4
	v_mov_b32_e32 v115, v4
	v_mov_b32_e32 v120, v4
	v_mov_b32_e32 v121, v4
	v_mov_b32_e32 v122, v4
	v_mov_b32_e32 v123, v4
	v_mov_b32_e32 v128, v4
	v_mov_b32_e32 v129, v4
	v_mov_b32_e32 v130, v4
	v_mov_b32_e32 v131, v4
	.p2align	6

.Lks_wait:
	s_waitcnt vmcnt(0)
	v_pk_mul_f32 v[34:35], v[34:35], v[172:173] op_sel_hi:[1,0]
	v_pk_mul_f32 v[32:33], v[32:33], v[172:173] op_sel_hi:[1,0]
	v_pk_mul_f32 v[30:31], v[30:31], v[172:173] op_sel_hi:[1,0]
	v_pk_mul_f32 v[28:29], v[28:29], v[172:173] op_sel_hi:[1,0]
	v_pk_mul_f32 v[26:27], v[26:27], v[172:173] op_sel_hi:[1,0]
	v_pk_mul_f32 v[24:25], v[24:25], v[172:173] op_sel_hi:[1,0]
	v_pk_mul_f32 v[22:23], v[22:23], v[172:173] op_sel_hi:[1,0]
	v_pk_mul_f32 v[20:21], v[20:21], v[172:173] op_sel_hi:[1,0]
	v_pk_mul_f32 v[50:51], v[50:51], v[170:171] op_sel_hi:[1,0]
	v_pk_mul_f32 v[48:49], v[48:49], v[170:171] op_sel_hi:[1,0]
	v_pk_mul_f32 v[46:47], v[46:47], v[170:171] op_sel_hi:[1,0]
	v_pk_mul_f32 v[44:45], v[44:45], v[170:171] op_sel_hi:[1,0]
	v_pk_mul_f32 v[42:43], v[42:43], v[170:171] op_sel_hi:[1,0]
	v_pk_mul_f32 v[40:41], v[40:41], v[170:171] op_sel_hi:[1,0]
	v_pk_mul_f32 v[38:39], v[38:39], v[170:171] op_sel_hi:[1,0]
	v_pk_mul_f32 v[36:37], v[36:37], v[170:171] op_sel_hi:[1,0]
	v_pk_mul_f32 v[66:67], v[66:67], v[168:169] op_sel_hi:[1,0]
	v_pk_mul_f32 v[64:65], v[64:65], v[168:169] op_sel_hi:[1,0]
	v_pk_mul_f32 v[62:63], v[62:63], v[168:169] op_sel_hi:[1,0]
	v_pk_mul_f32 v[60:61], v[60:61], v[168:169] op_sel_hi:[1,0]
	v_pk_mul_f32 v[58:59], v[58:59], v[168:169] op_sel_hi:[1,0]
	v_pk_mul_f32 v[56:57], v[56:57], v[168:169] op_sel_hi:[1,0]
	v_pk_mul_f32 v[54:55], v[54:55], v[168:169] op_sel_hi:[1,0]
	v_pk_mul_f32 v[52:53], v[52:53], v[168:169] op_sel_hi:[1,0]
	v_pk_mul_f32 v[82:83], v[82:83], v[166:167] op_sel_hi:[1,0]
	v_pk_mul_f32 v[80:81], v[80:81], v[166:167] op_sel_hi:[1,0]
	v_pk_mul_f32 v[78:79], v[78:79], v[166:167] op_sel_hi:[1,0]
	v_pk_mul_f32 v[76:77], v[76:77], v[166:167] op_sel_hi:[1,0]
	v_pk_mul_f32 v[74:75], v[74:75], v[166:167] op_sel_hi:[1,0]
	v_pk_mul_f32 v[72:73], v[72:73], v[166:167] op_sel_hi:[1,0]
	v_pk_mul_f32 v[70:71], v[70:71], v[166:167] op_sel_hi:[1,0]
	v_pk_mul_f32 v[68:69], v[68:69], v[166:167] op_sel_hi:[1,0]
	v_pk_mul_f32 v[98:99], v[98:99], v[164:165] op_sel_hi:[1,0]
	v_pk_mul_f32 v[96:97], v[96:97], v[164:165] op_sel_hi:[1,0]
	v_pk_mul_f32 v[94:95], v[94:95], v[164:165] op_sel_hi:[1,0]
	v_pk_mul_f32 v[92:93], v[92:93], v[164:165] op_sel_hi:[1,0]
	v_pk_mul_f32 v[90:91], v[90:91], v[164:165] op_sel_hi:[1,0]
	v_pk_mul_f32 v[88:89], v[88:89], v[164:165] op_sel_hi:[1,0]
	v_pk_mul_f32 v[86:87], v[86:87], v[164:165] op_sel_hi:[1,0]
	v_pk_mul_f32 v[84:85], v[84:85], v[164:165] op_sel_hi:[1,0]
	v_pk_mul_f32 v[114:115], v[114:115], v[2:3] op_sel_hi:[1,0]
	v_pk_mul_f32 v[112:113], v[112:113], v[2:3] op_sel_hi:[1,0]
	v_pk_mul_f32 v[110:111], v[110:111], v[2:3] op_sel_hi:[1,0]
	v_pk_mul_f32 v[108:109], v[108:109], v[2:3] op_sel_hi:[1,0]
	v_pk_mul_f32 v[106:107], v[106:107], v[2:3] op_sel_hi:[1,0]
	v_pk_mul_f32 v[104:105], v[104:105], v[2:3] op_sel_hi:[1,0]
	v_pk_mul_f32 v[102:103], v[102:103], v[2:3] op_sel_hi:[1,0]
	v_pk_mul_f32 v[100:101], v[100:101], v[2:3] op_sel_hi:[1,0]
	v_pk_mul_f32 v[130:131], v[130:131], v[0:1] op_sel_hi:[1,0]
	v_pk_mul_f32 v[128:129], v[128:129], v[0:1] op_sel_hi:[1,0]
	v_pk_mul_f32 v[126:127], v[126:127], v[0:1] op_sel_hi:[1,0]
	v_pk_mul_f32 v[124:125], v[124:125], v[0:1] op_sel_hi:[1,0]
	v_pk_mul_f32 v[122:123], v[122:123], v[0:1] op_sel_hi:[1,0]
	v_pk_mul_f32 v[120:121], v[120:121], v[0:1] op_sel_hi:[1,0]
	v_pk_mul_f32 v[118:119], v[118:119], v[0:1] op_sel_hi:[1,0]
	v_pk_mul_f32 v[116:117], v[116:117], v[0:1] op_sel_hi:[1,0]
	v_pk_mul_f32 v[18:19], v[18:19], v[162:163] op_sel_hi:[1,0]
	v_pk_mul_f32 v[16:17], v[16:17], v[162:163] op_sel_hi:[1,0]
	v_pk_mul_f32 v[14:15], v[14:15], v[162:163] op_sel_hi:[1,0]
	v_pk_mul_f32 v[12:13], v[12:13], v[162:163] op_sel_hi:[1,0]
	v_pk_mul_f32 v[10:11], v[10:11], v[162:163] op_sel_hi:[1,0]
	v_pk_mul_f32 v[8:9], v[8:9], v[162:163] op_sel_hi:[1,0]
	v_pk_mul_f32 v[6:7], v[6:7], v[162:163] op_sel_hi:[1,0]
	v_pk_mul_f32 v[4:5], v[4:5], v[162:163] op_sel_hi:[1,0]
	.p2align	6

.LBB0_810:
	s_add_u32 s13, s24, 0x100
	v_mov_b32_e32 v4, 0
	s_addc_u32 s14, s25, 0
	s_mov_b32 s15, -2
	v_mov_b32_e32 v5, v4
	v_mov_b32_e32 v6, v4
	v_mov_b32_e32 v7, v4
	v_mov_b32_e32 v8, v4
	s_waitcnt lgkmcnt(0)
	v_mov_b32_e32 v9, v4
	v_mov_b32_e32 v10, v4
	v_mov_b32_e32 v11, v4
	v_mov_b32_e32 v20, v4
	v_mov_b32_e32 v21, v4
	v_mov_b32_e32 v22, v4
	v_mov_b32_e32 v23, v4
	v_mov_b32_e32 v24, v4
	v_mov_b32_e32 v25, v4
	v_mov_b32_e32 v26, v4
	v_mov_b32_e32 v27, v4
	v_mov_b32_e32 v36, v4
	v_mov_b32_e32 v37, v4
	v_mov_b32_e32 v38, v4
	v_mov_b32_e32 v39, v4
	v_mov_b32_e32 v40, v4
	v_mov_b32_e32 v41, v4
	v_mov_b32_e32 v42, v4
	v_mov_b32_e32 v43, v4
	v_mov_b32_e32 v52, v4
	v_mov_b32_e32 v53, v4
	v_mov_b32_e32 v54, v4
	v_mov_b32_e32 v55, v4
	v_mov_b32_e32 v56, v4
	v_mov_b32_e32 v57, v4
	v_mov_b32_e32 v58, v4
	v_mov_b32_e32 v59, v4
	v_mov_b32_e32 v12, v4
	v_mov_b32_e32 v13, v4
	v_mov_b32_e32 v14, v4
	v_mov_b32_e32 v15, v4
	v_mov_b32_e32 v16, v4
	v_mov_b32_e32 v17, v4
	v_mov_b32_e32 v18, v4
	v_mov_b32_e32 v19, v4
	v_mov_b32_e32 v28, v4
	v_mov_b32_e32 v29, v4
	v_mov_b32_e32 v30, v4
	v_mov_b32_e32 v31, v4
	v_mov_b32_e32 v32, v4
	v_mov_b32_e32 v33, v4
	v_mov_b32_e32 v34, v4
	v_mov_b32_e32 v35, v4
	v_mov_b32_e32 v44, v4
	v_mov_b32_e32 v45, v4
	v_mov_b32_e32 v46, v4
	v_mov_b32_e32 v47, v4
	v_mov_b32_e32 v48, v4
	v_mov_b32_e32 v49, v4
	v_mov_b32_e32 v50, v4
	v_mov_b32_e32 v51, v4
	v_mov_b32_e32 v60, v4
	v_mov_b32_e32 v61, v4
	v_mov_b32_e32 v62, v4
	v_mov_b32_e32 v63, v4
	v_mov_b32_e32 v64, v4
	v_mov_b32_e32 v65, v4
	v_mov_b32_e32 v66, v4
	v_mov_b32_e32 v67, v4
	v_mov_b32_e32 v68, v4
	v_mov_b32_e32 v69, v4
	v_mov_b32_e32 v70, v4
	v_mov_b32_e32 v71, v4
	v_mov_b32_e32 v72, v4
	v_mov_b32_e32 v73, v4
	v_mov_b32_e32 v74, v4
	v_mov_b32_e32 v75, v4
	v_mov_b32_e32 v84, v4
	v_mov_b32_e32 v85, v4
	v_mov_b32_e32 v86, v4
	v_mov_b32_e32 v87, v4
	v_mov_b32_e32 v88, v4
	v_mov_b32_e32 v89, v4
	v_mov_b32_e32 v90, v4
	v_mov_b32_e32 v91, v4
	v_mov_b32_e32 v100, v4
	v_mov_b32_e32 v101, v4
	v_mov_b32_e32 v102, v4
	v_mov_b32_e32 v103, v4
	v_mov_b32_e32 v104, v4
	v_mov_b32_e32 v105, v4
	v_mov_b32_e32 v106, v4
	v_mov_b32_e32 v107, v4
	v_mov_b32_e32 v116, v4
	v_mov_b32_e32 v117, v4
	v_mov_b32_e32 v118, v4
	v_mov_b32_e32 v119, v4
	v_mov_b32_e32 v120, v4
	v_mov_b32_e32 v121, v4
	v_mov_b32_e32 v122, v4
	v_mov_b32_e32 v123, v4
	v_mov_b32_e32 v76, v4
	v_mov_b32_e32 v77, v4
	v_mov_b32_e32 v78, v4
	v_mov_b32_e32 v79, v4
	v_mov_b32_e32 v80, v4
	v_mov_b32_e32 v81, v4
	v_mov_b32_e32 v82, v4
	v_mov_b32_e32 v83, v4
	v_mov_b32_e32 v92, v4
	v_mov_b32_e32 v93, v4
	v_mov_b32_e32 v94, v4
	v_mov_b32_e32 v95, v4
	v_mov_b32_e32 v96, v4
	v_mov_b32_e32 v97, v4
	v_mov_b32_e32 v98, v4
	v_mov_b32_e32 v99, v4
	v_mov_b32_e32 v108, v4
	v_mov_b32_e32 v109, v4
	v_mov_b32_e32 v110, v4
	v_mov_b32_e32 v111, v4
	v_mov_b32_e32 v112, v4
	v_mov_b32_e32 v113, v4
	v_mov_b32_e32 v114, v4
	v_mov_b32_e32 v115, v4
	v_mov_b32_e32 v124, v4
	v_mov_b32_e32 v125, v4
	v_mov_b32_e32 v126, v4
	v_mov_b32_e32 v127, v4
	v_mov_b32_e32 v128, v4
	v_mov_b32_e32 v129, v4
	v_mov_b32_e32 v130, v4
	v_mov_b32_e32 v131, v4
	.p2align	6

.LBB0_927:
	s_ashr_i32 s7, s6, 31
	s_lshl_b64 s[10:11], s[6:7], 19
	s_add_u32 s10, s20, s10
	s_addc_u32 s11, s21, s11
	s_and_b64 s[14:15], s[38:39], exec
	s_cselect_b32 s7, s11, s23
	s_cselect_b32 s13, s10, s22
	s_ashr_i32 s5, s4, 31
	s_lshl_b64 s[14:15], s[4:5], 19
	s_add_u32 s14, s26, s14
	s_addc_u32 s15, s27, s15
	s_and_b64 s[18:19], s[38:39], exec
	s_cselect_b32 s5, s15, s43
	s_cselect_b32 s17, s14, s42
	s_add_u32 s40, s22, 0x40080
	s_addc_u32 s41, s23, 0
	s_add_u32 s42, s42, 0x100
	v_mov_b32_e32 v4, 0
	s_addc_u32 s43, s43, 0
	s_mov_b32 s51, -2
	v_mov_b32_e32 v5, v4
	v_mov_b32_e32 v6, v4
	v_mov_b32_e32 v7, v4
	v_mov_b32_e32 v8, v4
	v_mov_b32_e32 v9, v4
	v_mov_b32_e32 v10, v4
	v_mov_b32_e32 v11, v4
	v_mov_b32_e32 v16, v4
	v_mov_b32_e32 v17, v4
	v_mov_b32_e32 v18, v4
	v_mov_b32_e32 v19, v4
	v_mov_b32_e32 v24, v4
	v_mov_b32_e32 v25, v4
	v_mov_b32_e32 v26, v4
	v_mov_b32_e32 v27, v4
	v_mov_b32_e32 v32, v4
	v_mov_b32_e32 v33, v4
	v_mov_b32_e32 v34, v4
	v_mov_b32_e32 v35, v4
	v_mov_b32_e32 v40, v4
	v_mov_b32_e32 v41, v4
	v_mov_b32_e32 v42, v4
	v_mov_b32_e32 v43, v4
	v_mov_b32_e32 v48, v4
	v_mov_b32_e32 v49, v4
	v_mov_b32_e32 v50, v4
	v_mov_b32_e32 v51, v4
	v_mov_b32_e32 v56, v4
	v_mov_b32_e32 v57, v4
	v_mov_b32_e32 v58, v4
	v_mov_b32_e32 v59, v4
	v_mov_b32_e32 v12, v4
	v_mov_b32_e32 v13, v4
	v_mov_b32_e32 v14, v4
	v_mov_b32_e32 v15, v4
	v_mov_b32_e32 v20, v4
	v_mov_b32_e32 v21, v4
	v_mov_b32_e32 v22, v4
	v_mov_b32_e32 v23, v4
	v_mov_b32_e32 v28, v4
	v_mov_b32_e32 v29, v4
	v_mov_b32_e32 v30, v4
	v_mov_b32_e32 v31, v4
	v_mov_b32_e32 v36, v4
	v_mov_b32_e32 v37, v4
	v_mov_b32_e32 v38, v4
	v_mov_b32_e32 v39, v4
	v_mov_b32_e32 v44, v4
	v_mov_b32_e32 v45, v4
	v_mov_b32_e32 v46, v4
	v_mov_b32_e32 v47, v4
	v_mov_b32_e32 v52, v4
	v_mov_b32_e32 v53, v4
	v_mov_b32_e32 v54, v4
	v_mov_b32_e32 v55, v4
	v_mov_b32_e32 v60, v4
	v_mov_b32_e32 v61, v4
	v_mov_b32_e32 v62, v4
	v_mov_b32_e32 v63, v4
	v_mov_b32_e32 v64, v4
	v_mov_b32_e32 v65, v4
	v_mov_b32_e32 v66, v4
	v_mov_b32_e32 v67, v4
	v_mov_b32_e32 v68, v4
	v_mov_b32_e32 v69, v4
	v_mov_b32_e32 v70, v4
	v_mov_b32_e32 v71, v4
	v_mov_b32_e32 v72, v4
	v_mov_b32_e32 v73, v4
	v_mov_b32_e32 v74, v4
	v_mov_b32_e32 v75, v4
	v_mov_b32_e32 v80, v4
	v_mov_b32_e32 v81, v4
	v_mov_b32_e32 v82, v4
	v_mov_b32_e32 v83, v4
	v_mov_b32_e32 v88, v4
	v_mov_b32_e32 v89, v4
	v_mov_b32_e32 v90, v4
	v_mov_b32_e32 v91, v4
	v_mov_b32_e32 v96, v4
	v_mov_b32_e32 v97, v4
	v_mov_b32_e32 v98, v4
	v_mov_b32_e32 v99, v4
	v_mov_b32_e32 v104, v4
	v_mov_b32_e32 v105, v4
	v_mov_b32_e32 v106, v4
	v_mov_b32_e32 v107, v4
	v_mov_b32_e32 v112, v4
	v_mov_b32_e32 v113, v4
	v_mov_b32_e32 v114, v4
	v_mov_b32_e32 v115, v4
	v_mov_b32_e32 v120, v4
	v_mov_b32_e32 v121, v4
	v_mov_b32_e32 v122, v4
	v_mov_b32_e32 v123, v4
	v_mov_b32_e32 v76, v4
	v_mov_b32_e32 v77, v4
	v_mov_b32_e32 v78, v4
	v_mov_b32_e32 v79, v4
	v_mov_b32_e32 v84, v4
	v_mov_b32_e32 v85, v4
	v_mov_b32_e32 v86, v4
	v_mov_b32_e32 v87, v4
	v_mov_b32_e32 v92, v4
	v_mov_b32_e32 v93, v4
	v_mov_b32_e32 v94, v4
	v_mov_b32_e32 v95, v4
	v_mov_b32_e32 v100, v4
	v_mov_b32_e32 v101, v4
	v_mov_b32_e32 v102, v4
	v_mov_b32_e32 v103, v4
	v_mov_b32_e32 v108, v4
	v_mov_b32_e32 v109, v4
	v_mov_b32_e32 v110, v4
	v_mov_b32_e32 v111, v4
	v_mov_b32_e32 v116, v4
	v_mov_b32_e32 v117, v4
	v_mov_b32_e32 v118, v4
	v_mov_b32_e32 v119, v4
	v_mov_b32_e32 v124, v4
	v_mov_b32_e32 v125, v4
	v_mov_b32_e32 v126, v4
	v_mov_b32_e32 v127, v4
	v_mov_b32_e32 v128, v4
	v_mov_b32_e32 v129, v4
	v_mov_b32_e32 v130, v4
	v_mov_b32_e32 v131, v4
	s_waitcnt vmcnt(0)
	.p2align	6
